# gemm_core256 K-loops (inproj+gates) rescheduled: next-tile global loads issued right after the LDS-write barrier, fragments in spare VGPRs; on top of scan loop rewrite
# speedup vs baseline: 1.0151x; 1.0015x over previous
; #define MFMA32(a, b, c) __builtin_amdgcn_mfma_f32_32x32x16_bf16((a), (b), (c), 0, 0, 0)
; DI void gemm_core256(f32x16 (&acc)[4][2], const u16* __restrict__ A, int lda, const u16* __restrict__ W, int ldw, int K,
;                      u16* sA, u16* sW) {
;     ...
;   for (int kt = 0; kt < nk; kt++) {
; #pragma unroll
;     for (int i = 0; i < 8; i++) {
;       *(u32x4*)(sA + (lr + i * 32) * 72 + lc * 8) = ra[i];
;       if (i < 4) *(u32x4*)(sW + (lr + i * 32) * 72 + lc * 8) = rw[i];
;     }
;     __syncthreads();
;     if (kt + 1 < nk) {
; #pragma unroll
;       for (int i = 0; i < 8; i++) {
;         ra[i] = *(const u32x4*)(A + (aoff + (unsigned)(i * 32 * lda) + (unsigned)((kt + 1) * 64)));
;         if (i < 4) rw[i] = *(const u32x4*)(W + (woff + (unsigned)(i * 32 * ldw) + (unsigned)((kt + 1) * 64)));
;       }
;     }
; #pragma unroll
;     for (int ks = 0; ks < 4; ks++) {
;       bf16x8 af[4], bfv[2];
; #pragma unroll
;       for (int mi = 0; mi < 4; mi++) af[mi] = *(const bf16x8*)(sA + (wm * 128 + mi * 32 + r) * 72 + ks * 16 + h * 8);
; #pragma unroll
;       for (int ni = 0; ni < 2; ni++) bfv[ni] = *(const bf16x8*)(sW + (wn * 64 + ni * 32 + r) * 72 + ks * 16 + h * 8);
; #pragma unroll
;       for (int mi = 0; mi < 4; mi++)
; #pragma unroll
;         for (int ni = 0; ni < 2; ni++) acc[mi][ni] = MFMA32(af[mi], bfv[ni], acc[mi][ni]);
;     }
;     __syncthreads();
.LBB0_353:
	s_waitcnt vmcnt(0)
	ds_write_b128 v183, v[128:131]
	ds_write_b128 v183, v[132:135] offset:36864
	ds_write_b128 v183, v[136:139] offset:4608
	ds_write_b128 v183, v[140:143] offset:41472
	ds_write_b128 v183, v[144:147] offset:9216
	ds_write_b128 v183, v[148:151] offset:46080
	ds_write_b128 v183, v[152:155] offset:13824
	ds_write_b128 v183, v[156:159] offset:50688
	ds_write_b128 v183, v[164:167] offset:18432
	ds_write_b128 v183, v[160:163] offset:23040
	ds_write_b128 v183, v[168:171] offset:27648
	ds_write_b128 v183, v[172:175] offset:32256
	s_waitcnt lgkmcnt(0)
	s_barrier
	ds_read_b128 v[238:241], v182 offset:36864
	ds_read_b128 v[222:225], v181
	ds_read_b128 v[226:229], v181 offset:4608
	ds_read_b128 v[230:233], v181 offset:9216
	ds_read_b128 v[234:237], v179
	ds_read_b128 v[242:245], v182 offset:41472
	ds_read_b128 v[246:249], v182 offset:36896
	v_add_u32_e32 v250, s13, v178
	v_add_u32_e32 v176, 0x40, v250
	v_lshl_add_u64 v[128:129], v[176:177], 1, s[36:37]
	global_load_dwordx4 v[128:131], v[128:129], off
	v_add_u32_e32 v176, 0x40, v250
	v_lshl_add_u64 v[132:133], v[176:177], 1, s[38:39]
	global_load_dwordx4 v[132:135], v[132:133], off
	v_add_u32_e32 v176, 0x8040, v250
	v_lshl_add_u64 v[136:137], v[176:177], 1, s[36:37]
	global_load_dwordx4 v[136:139], v[136:137], off
	v_add_u32_e32 v176, 0x8040, v250
	v_lshl_add_u64 v[140:141], v[176:177], 1, s[38:39]
	global_load_dwordx4 v[140:143], v[140:141], off
	v_add_u32_e32 v176, 0x10040, v250
	v_lshl_add_u64 v[144:145], v[176:177], 1, s[36:37]
	global_load_dwordx4 v[144:147], v[144:145], off
	v_add_u32_e32 v176, 0x10040, v250
	v_lshl_add_u64 v[148:149], v[176:177], 1, s[38:39]
	global_load_dwordx4 v[148:151], v[148:149], off
	v_add_u32_e32 v176, 0x18040, v250
	v_lshl_add_u64 v[152:153], v[176:177], 1, s[36:37]
	global_load_dwordx4 v[152:155], v[152:153], off
	v_add_u32_e32 v176, 0x18040, v250
	v_lshl_add_u64 v[156:157], v[176:177], 1, s[38:39]
	global_load_dwordx4 v[156:159], v[156:157], off
	v_add_u32_e32 v176, 0x20040, v250
	v_lshl_add_u64 v[164:165], v[176:177], 1, s[36:37]
	global_load_dwordx4 v[164:167], v[164:165], off
	v_add_u32_e32 v176, 0x28040, v250
	v_lshl_add_u64 v[160:161], v[176:177], 1, s[36:37]
	global_load_dwordx4 v[160:163], v[160:161], off
	v_add_u32_e32 v176, 0x30040, v250
	v_lshl_add_u64 v[168:169], v[176:177], 1, s[36:37]
	global_load_dwordx4 v[168:171], v[168:169], off
	v_add_u32_e32 v176, 0x38040, v250
	v_lshl_add_u64 v[172:173], v[176:177], 1, s[36:37]
	global_load_dwordx4 v[172:175], v[172:173], off
	s_waitcnt lgkmcnt(5)
	v_mfma_f32_32x32x16_bf16 v[112:127], v[222:225], v[238:241], v[112:127]
	s_waitcnt lgkmcnt(4)
	v_mfma_f32_32x32x16_bf16 v[80:95], v[226:229], v[238:241], v[80:95]
	s_waitcnt lgkmcnt(3)
	v_mfma_f32_32x32x16_bf16 v[48:63], v[230:233], v[238:241], v[48:63]
	s_waitcnt lgkmcnt(2)
	v_mfma_f32_32x32x16_bf16 v[16:31], v[234:237], v[238:241], v[16:31]
	ds_read_b128 v[238:241], v182 offset:41504
	s_waitcnt lgkmcnt(2)
	v_mfma_f32_32x32x16_bf16 v[96:111], v[222:225], v[242:245], v[96:111]
	ds_read_b128 v[222:225], v181 offset:32
	v_mfma_f32_32x32x16_bf16 v[64:79], v[226:229], v[242:245], v[64:79]
	ds_read_b128 v[226:229], v181 offset:4640
	v_mfma_f32_32x32x16_bf16 v[32:47], v[230:233], v[242:245], v[32:47]
	ds_read_b128 v[230:233], v181 offset:9248
	v_mfma_f32_32x32x16_bf16 v[0:15], v[234:237], v[242:245], v[0:15]
	ds_read_b128 v[234:237], v179 offset:32
	ds_read_b128 v[242:245], v182 offset:36928
	s_waitcnt lgkmcnt(4)
	v_mfma_f32_32x32x16_bf16 v[112:127], v[222:225], v[246:249], v[112:127]
	s_waitcnt lgkmcnt(3)
	v_mfma_f32_32x32x16_bf16 v[80:95], v[226:229], v[246:249], v[80:95]
	s_waitcnt lgkmcnt(2)
	v_mfma_f32_32x32x16_bf16 v[48:63], v[230:233], v[246:249], v[48:63]
	s_waitcnt lgkmcnt(1)
	v_mfma_f32_32x32x16_bf16 v[16:31], v[234:237], v[246:249], v[16:31]
	ds_read_b128 v[246:249], v182 offset:41536
	v_mfma_f32_32x32x16_bf16 v[96:111], v[222:225], v[238:241], v[96:111]
	ds_read_b128 v[222:225], v181 offset:64
	v_mfma_f32_32x32x16_bf16 v[64:79], v[226:229], v[238:241], v[64:79]
	ds_read_b128 v[226:229], v181 offset:4672
	v_mfma_f32_32x32x16_bf16 v[32:47], v[230:233], v[238:241], v[32:47]
	ds_read_b128 v[230:233], v181 offset:9280
	v_mfma_f32_32x32x16_bf16 v[0:15], v[234:237], v[238:241], v[0:15]
	ds_read_b128 v[234:237], v179 offset:64
	ds_read_b128 v[238:241], v182 offset:36960
	s_waitcnt lgkmcnt(4)
	v_mfma_f32_32x32x16_bf16 v[112:127], v[222:225], v[242:245], v[112:127]
	s_waitcnt lgkmcnt(3)
	v_mfma_f32_32x32x16_bf16 v[80:95], v[226:229], v[242:245], v[80:95]
	s_waitcnt lgkmcnt(2)
	v_mfma_f32_32x32x16_bf16 v[48:63], v[230:233], v[242:245], v[48:63]
	s_waitcnt lgkmcnt(1)
	v_mfma_f32_32x32x16_bf16 v[16:31], v[234:237], v[242:245], v[16:31]
	ds_read_b128 v[242:245], v182 offset:41568
	v_mfma_f32_32x32x16_bf16 v[96:111], v[222:225], v[246:249], v[96:111]
	ds_read_b128 v[222:225], v181 offset:96
	v_mfma_f32_32x32x16_bf16 v[64:79], v[226:229], v[246:249], v[64:79]
	ds_read_b128 v[226:229], v181 offset:4704
	v_mfma_f32_32x32x16_bf16 v[32:47], v[230:233], v[246:249], v[32:47]
	ds_read_b128 v[230:233], v181 offset:9312
	v_mfma_f32_32x32x16_bf16 v[0:15], v[234:237], v[246:249], v[0:15]
	ds_read_b128 v[234:237], v179 offset:96
	s_waitcnt lgkmcnt(3)
	v_mfma_f32_32x32x16_bf16 v[112:127], v[222:225], v[238:241], v[112:127]
	s_waitcnt lgkmcnt(2)
	v_mfma_f32_32x32x16_bf16 v[80:95], v[226:229], v[238:241], v[80:95]
	s_waitcnt lgkmcnt(1)
	v_mfma_f32_32x32x16_bf16 v[48:63], v[230:233], v[238:241], v[48:63]
	s_waitcnt lgkmcnt(0)
	v_mfma_f32_32x32x16_bf16 v[16:31], v[234:237], v[238:241], v[16:31]
	v_mfma_f32_32x32x16_bf16 v[96:111], v[222:225], v[242:245], v[96:111]
	v_mfma_f32_32x32x16_bf16 v[64:79], v[226:229], v[242:245], v[64:79]
	v_mfma_f32_32x32x16_bf16 v[32:47], v[230:233], v[242:245], v[32:47]
	v_mfma_f32_32x32x16_bf16 v[0:15], v[234:237], v[242:245], v[0:15]
	s_add_i32 s13, s13, 64
	s_cmpk_lg_i32 s13, 0x3c0
	s_barrier
; #define MFMA32(a, b, c) __builtin_amdgcn_mfma_f32_32x32x16_bf16((a), (b), (c), 0, 0, 0)
; DI int otid() { int t; asm volatile("v_mov_b32 %0, %1" : "=v"(t) : "v"((int)threadIdx.x)); return t; }
; DI void gemm_core256(f32x16 (&acc)[4][2], const u16* __restrict__ A, int lda, const u16* __restrict__ W, int ldw, int K,
;                      u16* sA, u16* sW) {
;     ...
;   for (int kt = 0; kt < nk; kt++) {
; #pragma unroll
;     for (int i = 0; i < 8; i++) {
;       *(u32x4*)(sA + (lr + i * 32) * 72 + lc * 8) = ra[i];
;       if (i < 4) *(u32x4*)(sW + (lr + i * 32) * 72 + lc * 8) = rw[i];
;     }
;     __syncthreads();
;     if (kt + 1 < nk) {
; #pragma unroll
;       for (int i = 0; i < 8; i++) {
;         ra[i] = *(const u32x4*)(A + (aoff + (unsigned)(i * 32 * lda) + (unsigned)((kt + 1) * 64)));
;         if (i < 4) rw[i] = *(const u32x4*)(W + (woff + (unsigned)(i * 32 * ldw) + (unsigned)((kt + 1) * 64)));
;       }
;     }
; #pragma unroll
;     for (int ks = 0; ks < 4; ks++) {
;       bf16x8 af[4], bfv[2];
; #pragma unroll
;       for (int mi = 0; mi < 4; mi++) af[mi] = *(const bf16x8*)(sA + (wm * 128 + mi * 32 + r) * 72 + ks * 16 + h * 8);
; #pragma unroll
;       for (int ni = 0; ni < 2; ni++) bfv[ni] = *(const bf16x8*)(sW + (wn * 64 + ni * 32 + r) * 72 + ks * 16 + h * 8);
; #pragma unroll
;       for (int mi = 0; mi < 4; mi++)
; #pragma unroll
;         for (int ni = 0; ni < 2; ni++) acc[mi][ni] = MFMA32(af[mi], bfv[ni], acc[mi][ni]);
;     }
;     __syncthreads();
;   }
; }
; DI void dump_acc256(const f32x16 (&acc)[4][2], float* sC, int hf) {
;   const int tid = otid(), lane = tid & 63, wv = tid >> 6, wm = wv >> 1, wn = wv & 1;
;   const int r = lane & 31, h = lane >> 5;
;   if (wm == hf) {
	s_cbranch_scc1 .LBB0_353
	s_waitcnt vmcnt(11)
	ds_write_b128 v183, v[128:131]
	s_waitcnt vmcnt(10)
	ds_write_b128 v183, v[132:135] offset:36864
	s_waitcnt vmcnt(9)
	ds_write_b128 v183, v[136:139] offset:4608
	s_waitcnt vmcnt(8)
	ds_write_b128 v183, v[140:143] offset:41472
	s_waitcnt vmcnt(7)
	ds_write_b128 v183, v[144:147] offset:9216
	s_waitcnt vmcnt(6)
	ds_write_b128 v183, v[148:151] offset:46080
	s_waitcnt vmcnt(5)
	ds_write_b128 v183, v[152:155] offset:13824
	s_waitcnt vmcnt(4)
	ds_write_b128 v183, v[156:159] offset:50688
	s_waitcnt vmcnt(3)
	ds_write_b128 v183, v[164:167] offset:18432
	s_waitcnt vmcnt(2)
	ds_write_b128 v183, v[160:163] offset:23040
	s_waitcnt vmcnt(1)
	ds_write_b128 v183, v[168:171] offset:27648
	s_waitcnt vmcnt(0)
	ds_write_b128 v183, v[172:175] offset:32256
	s_waitcnt lgkmcnt(0)
	s_barrier
	ds_read_b128 v[128:131], v181
	ds_read_b128 v[132:135], v182 offset:36864
	ds_read_b128 v[136:139], v181 offset:32
	ds_read_b128 v[140:143], v182 offset:36896
	ds_read_b128 v[144:147], v182 offset:41472
	ds_read_b128 v[148:151], v182 offset:41504
	s_waitcnt lgkmcnt(4)
	v_mfma_f32_32x32x16_bf16 v[112:127], v[128:131], v[132:135], v[112:127]
	s_movk_i32 s13, 0x80
	s_waitcnt lgkmcnt(1)
	v_mfma_f32_32x32x16_bf16 v[96:111], v[128:131], v[144:147], v[96:111]
	ds_read_b128 v[128:131], v181 offset:4608
	ds_read_b128 v[152:155], v181 offset:4640
	s_waitcnt lgkmcnt(1)
	v_mfma_f32_32x32x16_bf16 v[80:95], v[128:131], v[132:135], v[80:95]
	v_mfma_f32_32x32x16_bf16 v[64:79], v[128:131], v[144:147], v[64:79]
	ds_read_b128 v[128:131], v181 offset:9216
	ds_read_b128 v[156:159], v181 offset:9248
	s_waitcnt lgkmcnt(1)
	v_mfma_f32_32x32x16_bf16 v[48:63], v[128:131], v[132:135], v[48:63]
	v_mfma_f32_32x32x16_bf16 v[32:47], v[128:131], v[144:147], v[32:47]
	ds_read_b128 v[128:131], v179
	ds_read_b128 v[160:163], v179 offset:32
	s_waitcnt lgkmcnt(1)
	v_mfma_f32_32x32x16_bf16 v[16:31], v[128:131], v[132:135], v[16:31]
	v_mfma_f32_32x32x16_bf16 v[0:15], v[128:131], v[144:147], v[0:15]
	v_mfma_f32_32x32x16_bf16 v[112:127], v[136:139], v[140:143], v[112:127]
	v_mfma_f32_32x32x16_bf16 v[96:111], v[136:139], v[148:151], v[96:111]
	v_mfma_f32_32x32x16_bf16 v[80:95], v[152:155], v[140:143], v[80:95]
	v_mfma_f32_32x32x16_bf16 v[64:79], v[152:155], v[148:151], v[64:79]
	v_mfma_f32_32x32x16_bf16 v[48:63], v[156:159], v[140:143], v[48:63]
	v_mfma_f32_32x32x16_bf16 v[32:47], v[156:159], v[148:151], v[32:47]
	s_waitcnt lgkmcnt(0)
	v_mfma_f32_32x32x16_bf16 v[16:31], v[160:163], v[140:143], v[16:31]
	ds_read_b128 v[128:131], v181 offset:64
	ds_read_b128 v[132:135], v182 offset:36928
	ds_read_b128 v[136:139], v181 offset:96
	ds_read_b128 v[140:143], v182 offset:36960
	v_mfma_f32_32x32x16_bf16 v[0:15], v[160:163], v[148:151], v[0:15]
	ds_read_b128 v[144:147], v182 offset:41536
	ds_read_b128 v[148:151], v182 offset:41568
	s_waitcnt lgkmcnt(4)
	v_mfma_f32_32x32x16_bf16 v[112:127], v[128:131], v[132:135], v[112:127]
	s_waitcnt lgkmcnt(1)
	v_mfma_f32_32x32x16_bf16 v[96:111], v[128:131], v[144:147], v[96:111]
	ds_read_b128 v[128:131], v181 offset:4672
	ds_read_b128 v[152:155], v181 offset:4704
	s_waitcnt lgkmcnt(1)
	v_mfma_f32_32x32x16_bf16 v[80:95], v[128:131], v[132:135], v[80:95]
	v_mfma_f32_32x32x16_bf16 v[64:79], v[128:131], v[144:147], v[64:79]
	ds_read_b128 v[128:131], v181 offset:9280
	ds_read_b128 v[156:159], v181 offset:9312
	s_waitcnt lgkmcnt(1)
	v_mfma_f32_32x32x16_bf16 v[48:63], v[128:131], v[132:135], v[48:63]
	v_mfma_f32_32x32x16_bf16 v[32:47], v[128:131], v[144:147], v[32:47]
	ds_read_b128 v[128:131], v179 offset:64
	ds_read_b128 v[160:163], v179 offset:96
	s_waitcnt lgkmcnt(0)
	s_barrier
	v_mfma_f32_32x32x16_bf16 v[16:31], v[128:131], v[132:135], v[16:31]
	v_mfma_f32_32x32x16_bf16 v[0:15], v[128:131], v[144:147], v[0:15]
	v_mov_b32 v128, v198
	s_nop 0
	v_cmp_gt_u32_e32 vcc, s13, v128
	v_mfma_f32_32x32x16_bf16 v[112:127], v[136:139], v[140:143], v[112:127]
	v_mfma_f32_32x32x16_bf16 v[96:111], v[136:139], v[148:151], v[96:111]
	v_mfma_f32_32x32x16_bf16 v[80:95], v[152:155], v[140:143], v[80:95]
	v_mfma_f32_32x32x16_bf16 v[64:79], v[152:155], v[148:151], v[64:79]
	v_mfma_f32_32x32x16_bf16 v[48:63], v[156:159], v[140:143], v[48:63]
	v_mfma_f32_32x32x16_bf16 v[32:47], v[156:159], v[148:151], v[32:47]
	v_mfma_f32_32x32x16_bf16 v[16:31], v[160:163], v[140:143], v[16:31]
	v_mfma_f32_32x32x16_bf16 v[0:15], v[160:163], v[148:151], v[0:15]
	s_and_saveexec_b64 s[36:37], vcc
	s_cbranch_execz .LBB0_356
; DI int otid() { int t; asm volatile("v_mov_b32 %0, %1" : "=v"(t) : "v"((int)threadIdx.x)); return t; }
; DI void dump_acc256(const f32x16 (&acc)[4][2], float* sC, int hf) {
;   const int tid = otid(), lane = tid & 63, wv = tid >> 6, wm = wv >> 1, wn = wv & 1;
;   const int r = lane & 31, h = lane >> 5;
;   if (wm == hf) {
; #pragma unroll
;     for (int mi = 0; mi < 4; mi++)
; #pragma unroll
;       for (int ni = 0; ni < 2; ni++)
; #pragma unroll
;         for (int i = 0; i < 16; i++) {
;           int row = mi * 32 + (i & 3) + 8 * (i >> 2) + 4 * h;
;           int col = wn * 64 + ni * 32 + r;
;           sC[row * CP + col] = acc[mi][ni][i];
;         }
;   }
; }
	v_lshrrev_b32_e32 v129, 3, v128
	v_and_b32_e32 v129, 4, v129
	v_and_b32_e32 v128, 0x5f, v128
	v_mul_u32_u24_e32 v129, 0x210, v129
	v_lshl_add_u32 v128, v128, 2, v129
	v_add_u32_e32 v129, 0x400, v128
	ds_write2_b32 v128, v112, v96 offset1:32
	ds_write2_b32 v128, v113, v97 offset0:132 offset1:164
	ds_write2_b32 v129, v114, v98 offset0:8 offset1:40
	ds_write2_b32 v129, v115, v99 offset0:140 offset1:172
	v_add_u32_e32 v129, 0x1000, v128
	ds_write2_b32 v129, v116, v100 offset0:32 offset1:64
	ds_write2_b32 v129, v117, v101 offset0:164 offset1:196
	v_add_u32_e32 v129, 0x1400, v128
	ds_write2_b32 v129, v118, v102 offset0:40 offset1:72
	ds_write2_b32 v129, v119, v103 offset0:172 offset1:204
	v_add_u32_e32 v129, 0x2000, v128
	ds_write2_b32 v129, v120, v104 offset0:64 offset1:96
	ds_write2_b32 v129, v121, v105 offset0:196 offset1:228
	v_add_u32_e32 v129, 0x2400, v128
	ds_write2_b32 v129, v122, v106 offset0:72 offset1:104
	ds_write2_b32 v129, v123, v107 offset0:204 offset1:236
	v_add_u32_e32 v129, 0x3000, v128
	ds_write2_b32 v129, v124, v108 offset0:96 offset1:128
	v_add_u32_e32 v129, 0x3200, v128
	ds_write2_b32 v129, v125, v109 offset0:100 offset1:132
	v_add_u32_e32 v129, 0x3400, v128
	ds_write2_b32 v129, v126, v110 offset0:104 offset1:136
	v_add_u32_e32 v129, 0x3600, v128
	ds_write2_b32 v129, v127, v111 offset0:108 offset1:140
	v_add_u32_e32 v129, 0x4000, v128
	ds_write2_b32 v129, v80, v64 offset0:128 offset1:160
	v_add_u32_e32 v129, 0x4400, v128
	ds_write2_b32 v129, v81, v65 offset0:4 offset1:36
	ds_write2_b32 v129, v82, v66 offset0:136 offset1:168
	v_add_u32_e32 v129, 0x4800, v128
	ds_write2_b32 v129, v83, v67 offset0:12 offset1:44
	v_add_u32_e32 v129, 0x5000, v128
	ds_write2_b32 v129, v84, v68 offset0:160 offset1:192
	v_add_u32_e32 v129, 0x5400, v128
	ds_write2_b32 v129, v85, v69 offset0:36 offset1:68
	ds_write2_b32 v129, v86, v70 offset0:168 offset1:200
	v_add_u32_e32 v129, 0x5800, v128
	ds_write2_b32 v129, v87, v71 offset0:44 offset1:76
	v_add_u32_e32 v129, 0x6000, v128
	ds_write2_b32 v129, v88, v72 offset0:192 offset1:224
	v_add_u32_e32 v129, 0x6400, v128
	ds_write2_b32 v129, v89, v73 offset0:68 offset1:100
	ds_write2_b32 v129, v90, v74 offset0:200 offset1:232
	v_add_u32_e32 v129, 0x6800, v128
	ds_write2_b32 v129, v91, v75 offset0:76 offset1:108
	v_add_u32_e32 v129, 0x7200, v128
	ds_write2_b32 v129, v92, v76 offset0:96 offset1:128
	v_add_u32_e32 v129, 0x7400, v128
	ds_write2_b32 v129, v93, v77 offset0:100 offset1:132
	v_add_u32_e32 v129, 0x7600, v128
	ds_write2_b32 v129, v94, v78 offset0:104 offset1:136
	v_add_u32_e32 v129, 0x7800, v128
	ds_write2_b32 v129, v95, v79 offset0:108 offset1:140
	v_add_u32_e32 v129, 0x8400, v128
	ds_write2_b32 v129, v48, v32 offset1:32
	ds_write2_b32 v129, v49, v33 offset0:132 offset1:164
	v_add_u32_e32 v129, 0x8800, v128
	ds_write2_b32 v129, v50, v34 offset0:8 offset1:40
	ds_write2_b32 v129, v51, v35 offset0:140 offset1:172
	v_add_u32_e32 v129, 0x9400, v128
	ds_write2_b32 v129, v52, v36 offset0:32 offset1:64
	ds_write2_b32 v129, v53, v37 offset0:164 offset1:196
	v_add_u32_e32 v129, 0x9800, v128
	ds_write2_b32 v129, v54, v38 offset0:40 offset1:72
	ds_write2_b32 v129, v55, v39 offset0:172 offset1:204
	v_add_u32_e32 v129, 0xa400, v128
	ds_write2_b32 v129, v56, v40 offset0:64 offset1:96
	ds_write2_b32 v129, v57, v41 offset0:196 offset1:228
	v_add_u32_e32 v129, 0xa800, v128
	ds_write2_b32 v129, v58, v42 offset0:72 offset1:104
	ds_write2_b32 v129, v59, v43 offset0:204 offset1:236
	v_add_u32_e32 v129, 0xb400, v128
	ds_write2_b32 v129, v60, v44 offset0:96 offset1:128
	v_add_u32_e32 v129, 0xb600, v128
	ds_write2_b32 v129, v61, v45 offset0:100 offset1:132
	v_add_u32_e32 v129, 0xb800, v128
	ds_write2_b32 v129, v62, v46 offset0:104 offset1:136
	v_add_u32_e32 v129, 0xba00, v128
	ds_write2_b32 v129, v63, v47 offset0:108 offset1:140
	v_add_u32_e32 v129, 0xc400, v128
	ds_write2_b32 v129, v16, v0 offset0:128 offset1:160
	v_add_u32_e32 v129, 0xc800, v128
	ds_write2_b32 v129, v17, v1 offset0:4 offset1:36
	ds_write2_b32 v129, v18, v2 offset0:136 offset1:168
	v_add_u32_e32 v129, 0xcc00, v128
	ds_write2_b32 v129, v19, v3 offset0:12 offset1:44
	v_add_u32_e32 v129, 0xd400, v128
	ds_write2_b32 v129, v20, v4 offset0:160 offset1:192
	v_add_u32_e32 v129, 0xd800, v128
	ds_write2_b32 v129, v21, v5 offset0:36 offset1:68
	ds_write2_b32 v129, v22, v6 offset0:168 offset1:200
	v_add_u32_e32 v129, 0xdc00, v128
	ds_write2_b32 v129, v23, v7 offset0:44 offset1:76
	v_add_u32_e32 v129, 0xe400, v128
	ds_write2_b32 v129, v24, v8 offset0:192 offset1:224
	v_add_u32_e32 v129, 0xe800, v128
	ds_write2_b32 v129, v25, v9 offset0:68 offset1:100
	ds_write2_b32 v129, v26, v10 offset0:200 offset1:232
	v_add_u32_e32 v129, 0xec00, v128
	ds_write2_b32 v129, v27, v11 offset0:76 offset1:108
	v_add_u32_e32 v129, 0xf600, v128
	ds_write2_b32 v129, v28, v12 offset0:96 offset1:128
	v_add_u32_e32 v129, 0xf800, v128
	ds_write2_b32 v129, v29, v13 offset0:100 offset1:132
	v_add_u32_e32 v129, 0xfa00, v128
	v_add_u32_e32 v128, 0xfc00, v128
	ds_write2_b32 v129, v30, v14 offset0:104 offset1:136
	ds_write2_b32 v128, v31, v15 offset0:108 offset1:140

; #define MFMA32(a, b, c) __builtin_amdgcn_mfma_f32_32x32x16_bf16((a), (b), (c), 0, 0, 0)
; DI void gemm_core256(f32x16 (&acc)[4][2], const u16* __restrict__ A, int lda, const u16* __restrict__ W, int ldw, int K,
;                      u16* sA, u16* sW) {
;     ...
;   for (int kt = 0; kt < nk; kt++) {
; #pragma unroll
;     for (int i = 0; i < 8; i++) {
;       *(u32x4*)(sA + (lr + i * 32) * 72 + lc * 8) = ra[i];
;       if (i < 4) *(u32x4*)(sW + (lr + i * 32) * 72 + lc * 8) = rw[i];
;     }
;     __syncthreads();
;     if (kt + 1 < nk) {
; #pragma unroll
;       for (int i = 0; i < 8; i++) {
;         ra[i] = *(const u32x4*)(A + (aoff + (unsigned)(i * 32 * lda) + (unsigned)((kt + 1) * 64)));
;         if (i < 4) rw[i] = *(const u32x4*)(W + (woff + (unsigned)(i * 32 * ldw) + (unsigned)((kt + 1) * 64)));
;       }
;     }
; #pragma unroll
;     for (int ks = 0; ks < 4; ks++) {
;       bf16x8 af[4], bfv[2];
; #pragma unroll
;       for (int mi = 0; mi < 4; mi++) af[mi] = *(const bf16x8*)(sA + (wm * 128 + mi * 32 + r) * 72 + ks * 16 + h * 8);
; #pragma unroll
;       for (int ni = 0; ni < 2; ni++) bfv[ni] = *(const bf16x8*)(sW + (wn * 64 + ni * 32 + r) * 72 + ks * 16 + h * 8);
; #pragma unroll
;       for (int mi = 0; mi < 4; mi++)
; #pragma unroll
;         for (int ni = 0; ni < 2; ni++) acc[mi][ni] = MFMA32(af[mi], bfv[ni], acc[mi][ni]);
;     }
;     __syncthreads();
.LBB0_968:
	s_waitcnt vmcnt(0)
	ds_write_b128 v221, v[128:131]
	ds_write_b128 v221, v[132:135] offset:36864
	ds_write_b128 v221, v[136:139] offset:4608
	ds_write_b128 v221, v[140:143] offset:41472
	ds_write_b128 v221, v[144:147] offset:9216
	ds_write_b128 v221, v[148:151] offset:46080
	ds_write_b128 v221, v[152:155] offset:13824
	ds_write_b128 v221, v[156:159] offset:50688
	ds_write_b128 v221, v[164:167] offset:18432
	ds_write_b128 v221, v[160:163] offset:23040
	ds_write_b128 v221, v[168:171] offset:27648
	ds_write_b128 v221, v[172:175] offset:32256
	s_waitcnt lgkmcnt(0)
	s_barrier
	ds_read_b128 v[238:241], v220 offset:36864
	ds_read_b128 v[222:225], v219
	ds_read_b128 v[226:229], v219 offset:4608
	ds_read_b128 v[230:233], v219 offset:9216
	ds_read_b128 v[234:237], v197
	ds_read_b128 v[242:245], v220 offset:41472
	ds_read_b128 v[246:249], v220 offset:36896
	v_add_u32_e32 v250, s13, v196
	v_add_u32_e32 v176, 0x40, v250
	v_lshl_add_u64 v[128:129], v[176:177], 1, s[36:37]
	global_load_dwordx4 v[128:131], v[128:129], off
	v_add_u32_e32 v176, 0x40, v250
	v_lshl_add_u64 v[132:133], v[176:177], 1, s[38:39]
	global_load_dwordx4 v[132:135], v[132:133], off
	v_add_u32_e32 v176, 0x8040, v250
	v_lshl_add_u64 v[136:137], v[176:177], 1, s[36:37]
	global_load_dwordx4 v[136:139], v[136:137], off
	v_add_u32_e32 v176, 0x8040, v250
	v_lshl_add_u64 v[140:141], v[176:177], 1, s[38:39]
	global_load_dwordx4 v[140:143], v[140:141], off
	v_add_u32_e32 v176, 0x10040, v250
	v_lshl_add_u64 v[144:145], v[176:177], 1, s[36:37]
	global_load_dwordx4 v[144:147], v[144:145], off
	v_add_u32_e32 v176, 0x10040, v250
	v_lshl_add_u64 v[148:149], v[176:177], 1, s[38:39]
	global_load_dwordx4 v[148:151], v[148:149], off
	v_add_u32_e32 v176, 0x18040, v250
	v_lshl_add_u64 v[152:153], v[176:177], 1, s[36:37]
	global_load_dwordx4 v[152:155], v[152:153], off
	v_add_u32_e32 v176, 0x18040, v250
	v_lshl_add_u64 v[156:157], v[176:177], 1, s[38:39]
	global_load_dwordx4 v[156:159], v[156:157], off
	v_add_u32_e32 v176, 0x20040, v250
	v_lshl_add_u64 v[164:165], v[176:177], 1, s[36:37]
	global_load_dwordx4 v[164:167], v[164:165], off
	v_add_u32_e32 v176, 0x28040, v250
	v_lshl_add_u64 v[160:161], v[176:177], 1, s[36:37]
	global_load_dwordx4 v[160:163], v[160:161], off
	v_add_u32_e32 v176, 0x30040, v250
	v_lshl_add_u64 v[168:169], v[176:177], 1, s[36:37]
	global_load_dwordx4 v[168:171], v[168:169], off
	v_add_u32_e32 v176, 0x38040, v250
	v_lshl_add_u64 v[172:173], v[176:177], 1, s[36:37]
	global_load_dwordx4 v[172:175], v[172:173], off
	s_waitcnt lgkmcnt(5)
	v_mfma_f32_32x32x16_bf16 v[112:127], v[222:225], v[238:241], v[112:127]
	s_waitcnt lgkmcnt(4)
	v_mfma_f32_32x32x16_bf16 v[80:95], v[226:229], v[238:241], v[80:95]
	s_waitcnt lgkmcnt(3)
	v_mfma_f32_32x32x16_bf16 v[48:63], v[230:233], v[238:241], v[48:63]
	s_waitcnt lgkmcnt(2)
	v_mfma_f32_32x32x16_bf16 v[16:31], v[234:237], v[238:241], v[16:31]
	ds_read_b128 v[238:241], v220 offset:41504
	s_waitcnt lgkmcnt(2)
	v_mfma_f32_32x32x16_bf16 v[96:111], v[222:225], v[242:245], v[96:111]
	ds_read_b128 v[222:225], v219 offset:32
	v_mfma_f32_32x32x16_bf16 v[64:79], v[226:229], v[242:245], v[64:79]
	ds_read_b128 v[226:229], v219 offset:4640
	v_mfma_f32_32x32x16_bf16 v[32:47], v[230:233], v[242:245], v[32:47]
	ds_read_b128 v[230:233], v219 offset:9248
	v_mfma_f32_32x32x16_bf16 v[0:15], v[234:237], v[242:245], v[0:15]
	ds_read_b128 v[234:237], v197 offset:32
	ds_read_b128 v[242:245], v220 offset:36928
	s_waitcnt lgkmcnt(4)
	v_mfma_f32_32x32x16_bf16 v[112:127], v[222:225], v[246:249], v[112:127]
	s_waitcnt lgkmcnt(3)
	v_mfma_f32_32x32x16_bf16 v[80:95], v[226:229], v[246:249], v[80:95]
	s_waitcnt lgkmcnt(2)
	v_mfma_f32_32x32x16_bf16 v[48:63], v[230:233], v[246:249], v[48:63]
	s_waitcnt lgkmcnt(1)
	v_mfma_f32_32x32x16_bf16 v[16:31], v[234:237], v[246:249], v[16:31]
	ds_read_b128 v[246:249], v220 offset:41536
	v_mfma_f32_32x32x16_bf16 v[96:111], v[222:225], v[238:241], v[96:111]
	ds_read_b128 v[222:225], v219 offset:64
	v_mfma_f32_32x32x16_bf16 v[64:79], v[226:229], v[238:241], v[64:79]
	ds_read_b128 v[226:229], v219 offset:4672
	v_mfma_f32_32x32x16_bf16 v[32:47], v[230:233], v[238:241], v[32:47]
	ds_read_b128 v[230:233], v219 offset:9280
	v_mfma_f32_32x32x16_bf16 v[0:15], v[234:237], v[238:241], v[0:15]
	ds_read_b128 v[234:237], v197 offset:64
	ds_read_b128 v[238:241], v220 offset:36960
	s_waitcnt lgkmcnt(4)
	v_mfma_f32_32x32x16_bf16 v[112:127], v[222:225], v[242:245], v[112:127]
	s_waitcnt lgkmcnt(3)
	v_mfma_f32_32x32x16_bf16 v[80:95], v[226:229], v[242:245], v[80:95]
	s_waitcnt lgkmcnt(2)
	v_mfma_f32_32x32x16_bf16 v[48:63], v[230:233], v[242:245], v[48:63]
	s_waitcnt lgkmcnt(1)
	v_mfma_f32_32x32x16_bf16 v[16:31], v[234:237], v[242:245], v[16:31]
	ds_read_b128 v[242:245], v220 offset:41568
	v_mfma_f32_32x32x16_bf16 v[96:111], v[222:225], v[246:249], v[96:111]
	ds_read_b128 v[222:225], v219 offset:96
	v_mfma_f32_32x32x16_bf16 v[64:79], v[226:229], v[246:249], v[64:79]
	ds_read_b128 v[226:229], v219 offset:4704
	v_mfma_f32_32x32x16_bf16 v[32:47], v[230:233], v[246:249], v[32:47]
	ds_read_b128 v[230:233], v219 offset:9312
	v_mfma_f32_32x32x16_bf16 v[0:15], v[234:237], v[246:249], v[0:15]
	ds_read_b128 v[234:237], v197 offset:96
	s_waitcnt lgkmcnt(3)
	v_mfma_f32_32x32x16_bf16 v[112:127], v[222:225], v[238:241], v[112:127]
	s_waitcnt lgkmcnt(2)
	v_mfma_f32_32x32x16_bf16 v[80:95], v[226:229], v[238:241], v[80:95]
	s_waitcnt lgkmcnt(1)
	v_mfma_f32_32x32x16_bf16 v[48:63], v[230:233], v[238:241], v[48:63]
	s_waitcnt lgkmcnt(0)
	v_mfma_f32_32x32x16_bf16 v[16:31], v[234:237], v[238:241], v[16:31]
	v_mfma_f32_32x32x16_bf16 v[96:111], v[222:225], v[242:245], v[96:111]
	v_mfma_f32_32x32x16_bf16 v[64:79], v[226:229], v[242:245], v[64:79]
	v_mfma_f32_32x32x16_bf16 v[32:47], v[230:233], v[242:245], v[32:47]
	v_mfma_f32_32x32x16_bf16 v[0:15], v[234:237], v[242:245], v[0:15]
	s_add_i32 s13, s13, 64
	s_cmpk_lg_i32 s13, 0x3c0
	s_barrier
; #define MFMA32(a, b, c) __builtin_amdgcn_mfma_f32_32x32x16_bf16((a), (b), (c), 0, 0, 0)
; DI int otid() { int t; asm volatile("v_mov_b32 %0, %1" : "=v"(t) : "v"((int)threadIdx.x)); return t; }
; DI void gemm_core256(f32x16 (&acc)[4][2], const u16* __restrict__ A, int lda, const u16* __restrict__ W, int ldw, int K,
;                      u16* sA, u16* sW) {
;     ...
;   for (int kt = 0; kt < nk; kt++) {
; #pragma unroll
;     for (int i = 0; i < 8; i++) {
;       *(u32x4*)(sA + (lr + i * 32) * 72 + lc * 8) = ra[i];
;       if (i < 4) *(u32x4*)(sW + (lr + i * 32) * 72 + lc * 8) = rw[i];
;     }
;     __syncthreads();
;     if (kt + 1 < nk) {
; #pragma unroll
;       for (int i = 0; i < 8; i++) {
;         ra[i] = *(const u32x4*)(A + (aoff + (unsigned)(i * 32 * lda) + (unsigned)((kt + 1) * 64)));
;         if (i < 4) rw[i] = *(const u32x4*)(W + (woff + (unsigned)(i * 32 * ldw) + (unsigned)((kt + 1) * 64)));
;       }
;     }
; #pragma unroll
;     for (int ks = 0; ks < 4; ks++) {
;       bf16x8 af[4], bfv[2];
; #pragma unroll
;       for (int mi = 0; mi < 4; mi++) af[mi] = *(const bf16x8*)(sA + (wm * 128 + mi * 32 + r) * 72 + ks * 16 + h * 8);
; #pragma unroll
;       for (int ni = 0; ni < 2; ni++) bfv[ni] = *(const bf16x8*)(sW + (wn * 64 + ni * 32 + r) * 72 + ks * 16 + h * 8);
; #pragma unroll
;       for (int mi = 0; mi < 4; mi++)
; #pragma unroll
;         for (int ni = 0; ni < 2; ni++) acc[mi][ni] = MFMA32(af[mi], bfv[ni], acc[mi][ni]);
;     }
;     __syncthreads();
;   }
; }
; DI void dump_acc256(const f32x16 (&acc)[4][2], float* sC, int hf) {
;   const int tid = otid(), lane = tid & 63, wv = tid >> 6, wm = wv >> 1, wn = wv & 1;
;   const int r = lane & 31, h = lane >> 5;
;   if (wm == hf) {
	s_cbranch_scc1 .LBB0_968
	s_waitcnt vmcnt(11)
	ds_write_b128 v221, v[128:131]
	s_waitcnt vmcnt(10)
	ds_write_b128 v221, v[132:135] offset:36864
	s_waitcnt vmcnt(9)
	ds_write_b128 v221, v[136:139] offset:4608
	s_waitcnt vmcnt(8)
	ds_write_b128 v221, v[140:143] offset:41472
	s_waitcnt vmcnt(7)
	ds_write_b128 v221, v[144:147] offset:9216
	s_waitcnt vmcnt(6)
	ds_write_b128 v221, v[148:151] offset:46080
	s_waitcnt vmcnt(5)
	ds_write_b128 v221, v[152:155] offset:13824
	s_waitcnt vmcnt(4)
	ds_write_b128 v221, v[156:159] offset:50688
	s_waitcnt vmcnt(3)
	ds_write_b128 v221, v[164:167] offset:18432
	s_waitcnt vmcnt(2)
	ds_write_b128 v221, v[160:163] offset:23040
	s_waitcnt vmcnt(1)
	ds_write_b128 v221, v[168:171] offset:27648
	s_waitcnt vmcnt(0)
	ds_write_b128 v221, v[172:175] offset:32256
	s_waitcnt lgkmcnt(0)
	s_barrier
	ds_read_b128 v[128:131], v219
	ds_read_b128 v[132:135], v220 offset:36864
	ds_read_b128 v[136:139], v219 offset:32
	ds_read_b128 v[140:143], v220 offset:36896
	ds_read_b128 v[144:147], v220 offset:41472
	ds_read_b128 v[148:151], v220 offset:41504
	s_waitcnt lgkmcnt(4)
	v_mfma_f32_32x32x16_bf16 v[112:127], v[128:131], v[132:135], v[112:127]
	s_movk_i32 s13, 0x80
	s_waitcnt lgkmcnt(1)
	v_mfma_f32_32x32x16_bf16 v[96:111], v[128:131], v[144:147], v[96:111]
	ds_read_b128 v[128:131], v219 offset:4608
	ds_read_b128 v[152:155], v219 offset:4640
	s_waitcnt lgkmcnt(1)
	v_mfma_f32_32x32x16_bf16 v[80:95], v[128:131], v[132:135], v[80:95]
	v_mfma_f32_32x32x16_bf16 v[64:79], v[128:131], v[144:147], v[64:79]
	ds_read_b128 v[128:131], v219 offset:9216
	ds_read_b128 v[156:159], v219 offset:9248
	s_waitcnt lgkmcnt(1)
	v_mfma_f32_32x32x16_bf16 v[48:63], v[128:131], v[132:135], v[48:63]
	v_mfma_f32_32x32x16_bf16 v[32:47], v[128:131], v[144:147], v[32:47]
	ds_read_b128 v[128:131], v197
	ds_read_b128 v[160:163], v197 offset:32
	s_waitcnt lgkmcnt(1)
	v_mfma_f32_32x32x16_bf16 v[16:31], v[128:131], v[132:135], v[16:31]
	v_mfma_f32_32x32x16_bf16 v[0:15], v[128:131], v[144:147], v[0:15]
	v_mfma_f32_32x32x16_bf16 v[112:127], v[136:139], v[140:143], v[112:127]
	v_mfma_f32_32x32x16_bf16 v[96:111], v[136:139], v[148:151], v[96:111]
	v_mfma_f32_32x32x16_bf16 v[80:95], v[152:155], v[140:143], v[80:95]
	v_mfma_f32_32x32x16_bf16 v[64:79], v[152:155], v[148:151], v[64:79]
	v_mfma_f32_32x32x16_bf16 v[48:63], v[156:159], v[140:143], v[48:63]
	v_mfma_f32_32x32x16_bf16 v[32:47], v[156:159], v[148:151], v[32:47]
	s_waitcnt lgkmcnt(0)
	v_mfma_f32_32x32x16_bf16 v[16:31], v[160:163], v[140:143], v[16:31]
	ds_read_b128 v[128:131], v219 offset:64
	ds_read_b128 v[132:135], v220 offset:36928
	ds_read_b128 v[136:139], v219 offset:96
	ds_read_b128 v[140:143], v220 offset:36960
	v_mfma_f32_32x32x16_bf16 v[0:15], v[160:163], v[148:151], v[0:15]
	ds_read_b128 v[144:147], v220 offset:41536
	ds_read_b128 v[148:151], v220 offset:41568
	s_waitcnt lgkmcnt(4)
	v_mfma_f32_32x32x16_bf16 v[112:127], v[128:131], v[132:135], v[112:127]
	s_waitcnt lgkmcnt(1)
	v_mfma_f32_32x32x16_bf16 v[96:111], v[128:131], v[144:147], v[96:111]
	ds_read_b128 v[128:131], v219 offset:4672
	ds_read_b128 v[152:155], v219 offset:4704
	s_waitcnt lgkmcnt(1)
	v_mfma_f32_32x32x16_bf16 v[80:95], v[128:131], v[132:135], v[80:95]
	v_mfma_f32_32x32x16_bf16 v[64:79], v[128:131], v[144:147], v[64:79]
	ds_read_b128 v[128:131], v219 offset:9280
	ds_read_b128 v[156:159], v219 offset:9312
	s_waitcnt lgkmcnt(1)
	v_mfma_f32_32x32x16_bf16 v[48:63], v[128:131], v[132:135], v[48:63]
	v_mfma_f32_32x32x16_bf16 v[32:47], v[128:131], v[144:147], v[32:47]
	ds_read_b128 v[128:131], v197 offset:64
	ds_read_b128 v[160:163], v197 offset:96
	s_waitcnt lgkmcnt(0)
	s_barrier
	v_mfma_f32_32x32x16_bf16 v[16:31], v[128:131], v[132:135], v[16:31]
	v_mfma_f32_32x32x16_bf16 v[0:15], v[128:131], v[144:147], v[0:15]
	v_mov_b32 v128, v198
	s_nop 0
	v_cmp_gt_u32_e32 vcc, s13, v128
	v_mfma_f32_32x32x16_bf16 v[112:127], v[136:139], v[140:143], v[112:127]
	v_mfma_f32_32x32x16_bf16 v[96:111], v[136:139], v[148:151], v[96:111]
	v_mfma_f32_32x32x16_bf16 v[80:95], v[152:155], v[140:143], v[80:95]
	v_mfma_f32_32x32x16_bf16 v[64:79], v[152:155], v[148:151], v[64:79]
	v_mfma_f32_32x32x16_bf16 v[48:63], v[156:159], v[140:143], v[48:63]
	v_mfma_f32_32x32x16_bf16 v[32:47], v[156:159], v[148:151], v[32:47]
	v_mfma_f32_32x32x16_bf16 v[16:31], v[160:163], v[140:143], v[16:31]
	v_mfma_f32_32x32x16_bf16 v[0:15], v[160:163], v[148:151], v[0:15]
	s_and_saveexec_b64 s[36:37], vcc
	s_cbranch_execz .LBB0_971
; DI int otid() { int t; asm volatile("v_mov_b32 %0, %1" : "=v"(t) : "v"((int)threadIdx.x)); return t; }
; DI void dump_acc256(const f32x16 (&acc)[4][2], float* sC, int hf) {
;   const int tid = otid(), lane = tid & 63, wv = tid >> 6, wm = wv >> 1, wn = wv & 1;
;   const int r = lane & 31, h = lane >> 5;
;   if (wm == hf) {
; #pragma unroll
;     for (int mi = 0; mi < 4; mi++)
; #pragma unroll
;       for (int ni = 0; ni < 2; ni++)
; #pragma unroll
;         for (int i = 0; i < 16; i++) {
;           int row = mi * 32 + (i & 3) + 8 * (i >> 2) + 4 * h;
;           int col = wn * 64 + ni * 32 + r;
;           sC[row * CP + col] = acc[mi][ni][i];
;         }
;   }
; }
	v_lshrrev_b32_e32 v129, 3, v128
	v_and_b32_e32 v129, 4, v129
	v_and_b32_e32 v128, 0x5f, v128
	v_mul_u32_u24_e32 v129, 0x210, v129
	v_lshl_add_u32 v128, v128, 2, v129
	v_add_u32_e32 v129, 0x400, v128
	ds_write2_b32 v128, v112, v96 offset1:32
	ds_write2_b32 v128, v113, v97 offset0:132 offset1:164
	ds_write2_b32 v129, v114, v98 offset0:8 offset1:40
	ds_write2_b32 v129, v115, v99 offset0:140 offset1:172
	v_add_u32_e32 v129, 0x1000, v128
	ds_write2_b32 v129, v116, v100 offset0:32 offset1:64
	ds_write2_b32 v129, v117, v101 offset0:164 offset1:196
	v_add_u32_e32 v129, 0x1400, v128
	ds_write2_b32 v129, v118, v102 offset0:40 offset1:72
	ds_write2_b32 v129, v119, v103 offset0:172 offset1:204
	v_add_u32_e32 v129, 0x2000, v128
	ds_write2_b32 v129, v120, v104 offset0:64 offset1:96
	ds_write2_b32 v129, v121, v105 offset0:196 offset1:228
	v_add_u32_e32 v129, 0x2400, v128
	ds_write2_b32 v129, v122, v106 offset0:72 offset1:104
	ds_write2_b32 v129, v123, v107 offset0:204 offset1:236
	v_add_u32_e32 v129, 0x3000, v128
	ds_write2_b32 v129, v124, v108 offset0:96 offset1:128
	v_add_u32_e32 v129, 0x3200, v128
	ds_write2_b32 v129, v125, v109 offset0:100 offset1:132
	v_add_u32_e32 v129, 0x3400, v128
	ds_write2_b32 v129, v126, v110 offset0:104 offset1:136
	v_add_u32_e32 v129, 0x3600, v128
	ds_write2_b32 v129, v127, v111 offset0:108 offset1:140
	v_add_u32_e32 v129, 0x4000, v128
	ds_write2_b32 v129, v80, v64 offset0:128 offset1:160
	v_add_u32_e32 v129, 0x4400, v128
	ds_write2_b32 v129, v81, v65 offset0:4 offset1:36
	ds_write2_b32 v129, v82, v66 offset0:136 offset1:168
	v_add_u32_e32 v129, 0x4800, v128
	ds_write2_b32 v129, v83, v67 offset0:12 offset1:44
	v_add_u32_e32 v129, 0x5000, v128
	ds_write2_b32 v129, v84, v68 offset0:160 offset1:192
	v_add_u32_e32 v129, 0x5400, v128
	ds_write2_b32 v129, v85, v69 offset0:36 offset1:68
	ds_write2_b32 v129, v86, v70 offset0:168 offset1:200
	v_add_u32_e32 v129, 0x5800, v128
	ds_write2_b32 v129, v87, v71 offset0:44 offset1:76
	v_add_u32_e32 v129, 0x6000, v128
	ds_write2_b32 v129, v88, v72 offset0:192 offset1:224
	v_add_u32_e32 v129, 0x6400, v128
	ds_write2_b32 v129, v89, v73 offset0:68 offset1:100
	ds_write2_b32 v129, v90, v74 offset0:200 offset1:232
	v_add_u32_e32 v129, 0x6800, v128
	ds_write2_b32 v129, v91, v75 offset0:76 offset1:108
	v_add_u32_e32 v129, 0x7200, v128
	ds_write2_b32 v129, v92, v76 offset0:96 offset1:128
	v_add_u32_e32 v129, 0x7400, v128
	ds_write2_b32 v129, v93, v77 offset0:100 offset1:132
	v_add_u32_e32 v129, 0x7600, v128
	ds_write2_b32 v129, v94, v78 offset0:104 offset1:136
	v_add_u32_e32 v129, 0x7800, v128
	ds_write2_b32 v129, v95, v79 offset0:108 offset1:140
	v_add_u32_e32 v129, 0x8400, v128
	ds_write2_b32 v129, v48, v32 offset1:32
	ds_write2_b32 v129, v49, v33 offset0:132 offset1:164
	v_add_u32_e32 v129, 0x8800, v128
	ds_write2_b32 v129, v50, v34 offset0:8 offset1:40
	ds_write2_b32 v129, v51, v35 offset0:140 offset1:172
	v_add_u32_e32 v129, 0x9400, v128
	ds_write2_b32 v129, v52, v36 offset0:32 offset1:64
	ds_write2_b32 v129, v53, v37 offset0:164 offset1:196
	v_add_u32_e32 v129, 0x9800, v128
	ds_write2_b32 v129, v54, v38 offset0:40 offset1:72
	ds_write2_b32 v129, v55, v39 offset0:172 offset1:204
	v_add_u32_e32 v129, 0xa400, v128
	ds_write2_b32 v129, v56, v40 offset0:64 offset1:96
	ds_write2_b32 v129, v57, v41 offset0:196 offset1:228
	v_add_u32_e32 v129, 0xa800, v128
	ds_write2_b32 v129, v58, v42 offset0:72 offset1:104
	ds_write2_b32 v129, v59, v43 offset0:204 offset1:236
	v_add_u32_e32 v129, 0xb400, v128
	ds_write2_b32 v129, v60, v44 offset0:96 offset1:128
	v_add_u32_e32 v129, 0xb600, v128
	ds_write2_b32 v129, v61, v45 offset0:100 offset1:132
	v_add_u32_e32 v129, 0xb800, v128
	ds_write2_b32 v129, v62, v46 offset0:104 offset1:136
	v_add_u32_e32 v129, 0xba00, v128
	ds_write2_b32 v129, v63, v47 offset0:108 offset1:140
	v_add_u32_e32 v129, 0xc400, v128
	ds_write2_b32 v129, v16, v0 offset0:128 offset1:160
	v_add_u32_e32 v129, 0xc800, v128
	ds_write2_b32 v129, v17, v1 offset0:4 offset1:36
	ds_write2_b32 v129, v18, v2 offset0:136 offset1:168
	v_add_u32_e32 v129, 0xcc00, v128
	ds_write2_b32 v129, v19, v3 offset0:12 offset1:44
	v_add_u32_e32 v129, 0xd400, v128
	ds_write2_b32 v129, v20, v4 offset0:160 offset1:192
	v_add_u32_e32 v129, 0xd800, v128
	ds_write2_b32 v129, v21, v5 offset0:36 offset1:68
	ds_write2_b32 v129, v22, v6 offset0:168 offset1:200
	v_add_u32_e32 v129, 0xdc00, v128
	ds_write2_b32 v129, v23, v7 offset0:44 offset1:76
	v_add_u32_e32 v129, 0xe400, v128
	ds_write2_b32 v129, v24, v8 offset0:192 offset1:224
	v_add_u32_e32 v129, 0xe800, v128
	ds_write2_b32 v129, v25, v9 offset0:68 offset1:100
	ds_write2_b32 v129, v26, v10 offset0:200 offset1:232
	v_add_u32_e32 v129, 0xec00, v128
	ds_write2_b32 v129, v27, v11 offset0:76 offset1:108
	v_add_u32_e32 v129, 0xf600, v128
	ds_write2_b32 v129, v28, v12 offset0:96 offset1:128
	v_add_u32_e32 v129, 0xf800, v128
	ds_write2_b32 v129, v29, v13 offset0:100 offset1:132
	v_add_u32_e32 v129, 0xfa00, v128
	v_add_u32_e32 v128, 0xfc00, v128
	ds_write2_b32 v129, v30, v14 offset0:104 offset1:136
	ds_write2_b32 v128, v31, v15 offset0:108 offset1:140
